# proj and gate-up K-loops: back-edge rotation (counter, pointer increments, last-iteration selects and exit compare moved in front of the last load segment's wait+barrier) and the B-fragment LDS read b
# speedup vs baseline: 1.0039x; 1.0039x over previous
.LBB0_339:
	v_add_u32_e32 v229, 0x10000, v149
	s_add_i32 s19, s19, 1
	s_cmp_gt_u32 s19, 1
	s_cselect_b32 s32, 1, 0
	s_cmp_lt_u32 s19, 7
	s_cselect_b64 s[36:37], -1, 0
	s_add_i32 s24, s30, 4
	s_mov_b32 s26, s42
.LBB0_341:
	s_ashr_i32 s27, s26, 31
	s_lshl_b64 s[28:29], s[26:27], 20
	s_add_u32 s38, s6, s28
	s_addc_u32 s39, s7, s29
	s_and_b64 s[28:29], s[36:37], exec
	s_cselect_b32 s27, s39, s47
	s_cselect_b32 s28, s38, s46
	s_ashr_i32 s25, s24, 31
	s_lshl_b64 s[34:35], s[24:25], 20
	s_add_u32 s40, s8, s34
	s_addc_u32 s41, s9, s35
	s_and_b64 s[34:35], s[36:37], exec
	s_cselect_b32 s25, s41, s45
	s_cselect_b32 s29, s40, s44
	s_add_u32 s31, s44, 0x100
	s_addc_u32 s34, s45, 0
	s_add_u32 s44, s46, 0x80080
	s_addc_u32 s45, s47, 0
	s_mov_b32 s35, -2
	s_add_u32 s33, s44, 0xfff80080
	s_addc_u32 s43, s45, -1
	s_add_i32 s50, 0, 0x10000
	s_cmp_eq_u32 s35, 28
	s_cselect_b32 s49, s27, s43
	s_cselect_b32 s48, s28, s33
	s_cselect_b32 s47, s25, s34
	s_cselect_b32 s46, s29, s31
	s_add_i32 s33, 0, 0x14000
	ds_read_b128 v[154:157], v229
	ds_read_b128 v[168:171], v229 offset:1024
	ds_read_b128 v[172:175], v229 offset:2048
	ds_read_b128 v[176:179], v229 offset:3072
	ds_read_b128 v[180:183], v229 offset:16384
	ds_read_b128 v[184:187], v229 offset:17408
	ds_read_b128 v[188:191], v229 offset:18432
	ds_read_b128 v[192:195], v229 offset:19456
	s_add_i32 m0, s12, 0xc000
	ds_read_b128 v[196:199], v167
	ds_read_b128 v[200:203], v167 offset:1024
	ds_read_b128 v[204:207], v167 offset:2048
	ds_read_b128 v[208:211], v167 offset:3072
	ds_read_b128 v[212:215], v167 offset:4096
	ds_read_b128 v[216:219], v167 offset:5120
	ds_read_b128 v[220:223], v167 offset:6144
	ds_read_b128 v[224:227], v167 offset:7168
	global_load_lds_dwordx4 v140, s[44:45]
	s_add_i32 m0, s12, 0xe000
	s_nop 0
	global_load_lds_dwordx4 v138, s[44:45]
	s_cmp_lg_u32 s32, 0
	s_cbranch_scc1 .Lpj_skip1_p
	s_waitcnt vmcnt(8)

.Lpj_skip2_p:
	s_mov_b32 s32, 0
	s_waitcnt lgkmcnt(0)
	s_barrier
	s_setprio 1
	s_waitcnt lgkmcnt(0)
	v_mfma_f32_16x16x32_bf16 v[64:67], v[154:157], v[196:199], 0
	v_mfma_f32_16x16x32_bf16 v[60:63], v[172:175], v[196:199], 0
	v_mfma_f32_16x16x32_bf16 v[52:55], v[154:157], v[204:207], 0
	v_mfma_f32_16x16x32_bf16 v[44:47], v[172:175], v[204:207], 0
	v_mfma_f32_16x16x32_bf16 v[36:39], v[154:157], v[212:215], 0
	v_mfma_f32_16x16x32_bf16 v[28:31], v[172:175], v[212:215], 0
	v_mfma_f32_16x16x32_bf16 v[20:23], v[154:157], v[220:223], 0
	v_mfma_f32_16x16x32_bf16 v[12:15], v[172:175], v[220:223], 0
	v_mfma_f32_16x16x32_bf16 v[64:67], v[168:171], v[200:203], v[64:67]
	v_mfma_f32_16x16x32_bf16 v[60:63], v[176:179], v[200:203], v[60:63]
	v_mfma_f32_16x16x32_bf16 v[52:55], v[168:171], v[208:211], v[52:55]
	v_mfma_f32_16x16x32_bf16 v[44:47], v[176:179], v[208:211], v[44:47]
	v_mfma_f32_16x16x32_bf16 v[36:39], v[168:171], v[216:219], v[36:39]
	v_mfma_f32_16x16x32_bf16 v[28:31], v[176:179], v[216:219], v[28:31]
	v_mfma_f32_16x16x32_bf16 v[20:23], v[168:171], v[224:227], v[20:23]
	v_mfma_f32_16x16x32_bf16 v[12:15], v[176:179], v[224:227], v[12:15]
	v_mfma_f32_16x16x32_bf16 v[56:59], v[180:183], v[196:199], 0
	v_mfma_f32_16x16x32_bf16 v[48:51], v[188:191], v[196:199], 0
	v_mfma_f32_16x16x32_bf16 v[40:43], v[180:183], v[204:207], 0
	v_mfma_f32_16x16x32_bf16 v[32:35], v[188:191], v[204:207], 0
	v_mfma_f32_16x16x32_bf16 v[24:27], v[180:183], v[212:215], 0
	v_mfma_f32_16x16x32_bf16 v[16:19], v[188:191], v[212:215], 0
	v_mfma_f32_16x16x32_bf16 v[8:11], v[180:183], v[220:223], 0
	v_mfma_f32_16x16x32_bf16 v[4:7], v[188:191], v[220:223], 0
	v_mfma_f32_16x16x32_bf16 v[56:59], v[184:187], v[200:203], v[56:59]
	v_mfma_f32_16x16x32_bf16 v[48:51], v[192:195], v[200:203], v[48:51]
	v_mfma_f32_16x16x32_bf16 v[40:43], v[184:187], v[208:211], v[40:43]
	v_mfma_f32_16x16x32_bf16 v[32:35], v[192:195], v[208:211], v[32:35]
	v_mfma_f32_16x16x32_bf16 v[24:27], v[184:187], v[216:219], v[24:27]
	v_mfma_f32_16x16x32_bf16 v[16:19], v[192:195], v[216:219], v[16:19]
	v_mfma_f32_16x16x32_bf16 v[8:11], v[184:187], v[224:227], v[8:11]
	v_mfma_f32_16x16x32_bf16 v[4:7], v[192:195], v[224:227], v[4:7]
	s_setprio 0
	s_barrier
	s_add_i32 s33, 0, 0x18000
	s_add_i32 s43, 0, 0x1c000
	ds_read_b128 v[154:157], v229 offset:32768
	ds_read_b128 v[168:171], v229 offset:33792
	ds_read_b128 v[172:175], v229 offset:34816
	ds_read_b128 v[176:179], v229 offset:35840
	ds_read_b128 v[180:183], v229 offset:49152
	ds_read_b128 v[184:187], v229 offset:50176
	ds_read_b128 v[188:191], v229 offset:51200
	ds_read_b128 v[192:195], v229 offset:52224
	s_add_u32 s48, s48, 0x80000
	s_addc_u32 s49, s49, 0
	s_mov_b32 m0, s14
	ds_read_b128 v[196:199], v167 offset:32768
	ds_read_b128 v[200:203], v167 offset:33792
	ds_read_b128 v[204:207], v167 offset:34816
	ds_read_b128 v[208:211], v167 offset:35840
	ds_read_b128 v[212:215], v167 offset:36864
	ds_read_b128 v[216:219], v167 offset:37888
	ds_read_b128 v[220:223], v167 offset:38912
	ds_read_b128 v[224:227], v167 offset:39936
	global_load_lds_dwordx4 v134, s[48:49]
	s_mov_b32 m0, s15
	s_nop 0
	global_load_lds_dwordx4 v132, s[48:49]
	s_waitcnt vmcnt(8)
	s_waitcnt lgkmcnt(0)
	s_barrier
	s_setprio 1
	s_waitcnt lgkmcnt(0)
	v_mfma_f32_16x16x32_bf16 v[128:131], v[154:157], v[196:199], v[128:131]
	v_mfma_f32_16x16x32_bf16 v[124:127], v[172:175], v[196:199], v[124:127]
	v_mfma_f32_16x16x32_bf16 v[116:119], v[154:157], v[204:207], v[116:119]
	v_mfma_f32_16x16x32_bf16 v[108:111], v[172:175], v[204:207], v[108:111]
	v_mfma_f32_16x16x32_bf16 v[100:103], v[154:157], v[212:215], v[100:103]
	v_mfma_f32_16x16x32_bf16 v[92:95], v[172:175], v[212:215], v[92:95]
	v_mfma_f32_16x16x32_bf16 v[84:87], v[154:157], v[220:223], v[84:87]
	v_mfma_f32_16x16x32_bf16 v[76:79], v[172:175], v[220:223], v[76:79]
	v_mfma_f32_16x16x32_bf16 v[128:131], v[168:171], v[200:203], v[128:131]
	v_mfma_f32_16x16x32_bf16 v[124:127], v[176:179], v[200:203], v[124:127]
	v_mfma_f32_16x16x32_bf16 v[116:119], v[168:171], v[208:211], v[116:119]
	v_mfma_f32_16x16x32_bf16 v[108:111], v[176:179], v[208:211], v[108:111]
	v_mfma_f32_16x16x32_bf16 v[100:103], v[168:171], v[216:219], v[100:103]
	v_mfma_f32_16x16x32_bf16 v[92:95], v[176:179], v[216:219], v[92:95]
	v_mfma_f32_16x16x32_bf16 v[84:87], v[168:171], v[224:227], v[84:87]
	v_mfma_f32_16x16x32_bf16 v[76:79], v[176:179], v[224:227], v[76:79]
	v_mfma_f32_16x16x32_bf16 v[120:123], v[180:183], v[196:199], v[120:123]
	v_mfma_f32_16x16x32_bf16 v[112:115], v[188:191], v[196:199], v[112:115]
	v_mfma_f32_16x16x32_bf16 v[104:107], v[180:183], v[204:207], v[104:107]
	v_mfma_f32_16x16x32_bf16 v[96:99], v[188:191], v[204:207], v[96:99]
	v_mfma_f32_16x16x32_bf16 v[88:91], v[180:183], v[212:215], v[88:91]
	v_mfma_f32_16x16x32_bf16 v[80:83], v[188:191], v[212:215], v[80:83]
	v_mfma_f32_16x16x32_bf16 v[72:75], v[180:183], v[220:223], v[72:75]
	v_mfma_f32_16x16x32_bf16 v[68:71], v[188:191], v[220:223], v[68:71]
	v_mfma_f32_16x16x32_bf16 v[120:123], v[184:187], v[200:203], v[120:123]
	v_mfma_f32_16x16x32_bf16 v[112:115], v[192:195], v[200:203], v[112:115]
	v_mfma_f32_16x16x32_bf16 v[104:107], v[184:187], v[208:211], v[104:107]
	v_mfma_f32_16x16x32_bf16 v[96:99], v[192:195], v[208:211], v[96:99]
	v_mfma_f32_16x16x32_bf16 v[88:91], v[184:187], v[216:219], v[88:91]
	v_mfma_f32_16x16x32_bf16 v[80:83], v[192:195], v[216:219], v[80:83]
	v_mfma_f32_16x16x32_bf16 v[72:75], v[184:187], v[224:227], v[72:75]
	v_mfma_f32_16x16x32_bf16 v[68:71], v[192:195], v[224:227], v[68:71]
	s_setprio 0
	s_barrier
	s_add_i32 s33, s33, s10
	s_mov_b32 m0, s33
	ds_read_b128 v[196:199], v167 offset:49152
	ds_read_b128 v[200:203], v167 offset:50176
	ds_read_b128 v[204:207], v167 offset:51200
	ds_read_b128 v[208:211], v167 offset:52224
	ds_read_b128 v[212:215], v167 offset:53248
	ds_read_b128 v[216:219], v167 offset:54272
	ds_read_b128 v[220:223], v167 offset:55296
	ds_read_b128 v[224:227], v167 offset:56320
	s_add_u32 s100, s46, 0x80
	s_addc_u32 s101, s47, 0
	global_load_lds_dwordx4 v2, s[100:101]
	s_add_i32 m0, s33, 0x2000
	s_add_u32 s46, s46, 0x80080
	s_addc_u32 s47, s47, 0
	s_add_i32 s33, s43, s10
	s_add_u32 s100, s46, 0xfff80000
	s_addc_u32 s101, s47, -1
	global_load_lds_dwordx4 v0, s[100:101]
	s_mov_b32 m0, s33
	s_nop 0
	global_load_lds_dwordx4 v2, s[46:47]
	s_add_i32 m0, s33, 0x2000
	s_nop 0
	global_load_lds_dwordx4 v0, s[46:47]
	s_mov_b32 m0, s16
	s_nop 0
	s_add_u32 s100, s48, 0xfff80080
	s_addc_u32 s101, s49, -1
	global_load_lds_dwordx4 v134, s[100:101]
	s_mov_b32 m0, s17
	s_nop 0
	s_add_u32 s100, s48, 0xfff80080
	s_addc_u32 s101, s49, -1
	global_load_lds_dwordx4 v132, s[100:101]
	s_add_i32 s35, s35, 2
	s_add_u32 s31, s31, 0x100
	s_addc_u32 s34, s34, 0
	s_add_u32 s44, s44, 0x100
	s_addc_u32 s45, s45, 0
	s_add_u32 s33, s44, 0xfff80080
	s_addc_u32 s43, s45, -1
	s_cmp_eq_u32 s35, 28
	s_cselect_b32 s49, s27, s43
	s_cselect_b32 s48, s28, s33
	s_cselect_b32 s47, s25, s34
	s_cselect_b32 s46, s29, s31
	s_waitcnt vmcnt(8)
	s_waitcnt lgkmcnt(0)
	s_barrier
	s_setprio 1
	s_waitcnt lgkmcnt(0)
	v_mfma_f32_16x16x32_bf16 v[64:67], v[154:157], v[196:199], v[64:67]
	v_mfma_f32_16x16x32_bf16 v[60:63], v[172:175], v[196:199], v[60:63]
	v_mfma_f32_16x16x32_bf16 v[52:55], v[154:157], v[204:207], v[52:55]
	v_mfma_f32_16x16x32_bf16 v[44:47], v[172:175], v[204:207], v[44:47]
	v_mfma_f32_16x16x32_bf16 v[36:39], v[154:157], v[212:215], v[36:39]
	v_mfma_f32_16x16x32_bf16 v[28:31], v[172:175], v[212:215], v[28:31]
	v_mfma_f32_16x16x32_bf16 v[20:23], v[154:157], v[220:223], v[20:23]
	v_mfma_f32_16x16x32_bf16 v[12:15], v[172:175], v[220:223], v[12:15]
	v_mfma_f32_16x16x32_bf16 v[64:67], v[168:171], v[200:203], v[64:67]
	v_mfma_f32_16x16x32_bf16 v[60:63], v[176:179], v[200:203], v[60:63]
	v_mfma_f32_16x16x32_bf16 v[52:55], v[168:171], v[208:211], v[52:55]
	v_mfma_f32_16x16x32_bf16 v[44:47], v[176:179], v[208:211], v[44:47]
	v_mfma_f32_16x16x32_bf16 v[36:39], v[168:171], v[216:219], v[36:39]
	v_mfma_f32_16x16x32_bf16 v[28:31], v[176:179], v[216:219], v[28:31]
	v_mfma_f32_16x16x32_bf16 v[20:23], v[168:171], v[224:227], v[20:23]
	v_mfma_f32_16x16x32_bf16 v[12:15], v[176:179], v[224:227], v[12:15]
	v_mfma_f32_16x16x32_bf16 v[56:59], v[180:183], v[196:199], v[56:59]
	v_mfma_f32_16x16x32_bf16 v[48:51], v[188:191], v[196:199], v[48:51]
	v_mfma_f32_16x16x32_bf16 v[40:43], v[180:183], v[204:207], v[40:43]
	v_mfma_f32_16x16x32_bf16 v[32:35], v[188:191], v[204:207], v[32:35]
	v_mfma_f32_16x16x32_bf16 v[24:27], v[180:183], v[212:215], v[24:27]
	v_mfma_f32_16x16x32_bf16 v[16:19], v[188:191], v[212:215], v[16:19]
	v_mfma_f32_16x16x32_bf16 v[8:11], v[180:183], v[220:223], v[8:11]
	v_mfma_f32_16x16x32_bf16 v[4:7], v[188:191], v[220:223], v[4:7]
	v_mfma_f32_16x16x32_bf16 v[56:59], v[184:187], v[200:203], v[56:59]
	v_mfma_f32_16x16x32_bf16 v[48:51], v[192:195], v[200:203], v[48:51]
	v_mfma_f32_16x16x32_bf16 v[40:43], v[184:187], v[208:211], v[40:43]
	v_mfma_f32_16x16x32_bf16 v[32:35], v[192:195], v[208:211], v[32:35]
	v_mfma_f32_16x16x32_bf16 v[24:27], v[184:187], v[216:219], v[24:27]
	v_mfma_f32_16x16x32_bf16 v[16:19], v[192:195], v[216:219], v[16:19]
	v_mfma_f32_16x16x32_bf16 v[8:11], v[184:187], v[224:227], v[8:11]
	v_mfma_f32_16x16x32_bf16 v[4:7], v[192:195], v[224:227], v[4:7]
	s_setprio 0
	s_barrier
.LBB0_342:
	s_add_i32 s50, 0, 0x10000
	s_add_i32 s33, 0, 0x14000
	ds_read_b128 v[154:157], v229
	ds_read_b128 v[168:171], v229 offset:1024
	ds_read_b128 v[172:175], v229 offset:2048
	ds_read_b128 v[176:179], v229 offset:3072
	ds_read_b128 v[180:183], v229 offset:16384
	ds_read_b128 v[184:187], v229 offset:17408
	ds_read_b128 v[188:191], v229 offset:18432
	ds_read_b128 v[192:195], v229 offset:19456
	s_add_i32 m0, s12, 0xc000
	ds_read_b128 v[196:199], v167
	ds_read_b128 v[200:203], v167 offset:1024
	ds_read_b128 v[204:207], v167 offset:2048
	ds_read_b128 v[208:211], v167 offset:3072
	ds_read_b128 v[212:215], v167 offset:4096
	ds_read_b128 v[216:219], v167 offset:5120
	ds_read_b128 v[220:223], v167 offset:6144
	ds_read_b128 v[224:227], v167 offset:7168
	global_load_lds_dwordx4 v140, s[44:45]
	s_add_i32 m0, s12, 0xe000
	s_nop 0
	global_load_lds_dwordx4 v138, s[44:45]
	s_waitcnt vmcnt(8)
	s_waitcnt lgkmcnt(0)
	s_barrier
	s_setprio 1
	s_waitcnt lgkmcnt(0)
	v_mfma_f32_16x16x32_bf16 v[128:131], v[154:157], v[196:199], v[128:131]
	v_mfma_f32_16x16x32_bf16 v[124:127], v[172:175], v[196:199], v[124:127]
	v_mfma_f32_16x16x32_bf16 v[116:119], v[154:157], v[204:207], v[116:119]
	v_mfma_f32_16x16x32_bf16 v[108:111], v[172:175], v[204:207], v[108:111]
	v_mfma_f32_16x16x32_bf16 v[100:103], v[154:157], v[212:215], v[100:103]
	v_mfma_f32_16x16x32_bf16 v[92:95], v[172:175], v[212:215], v[92:95]
	v_mfma_f32_16x16x32_bf16 v[84:87], v[154:157], v[220:223], v[84:87]
	v_mfma_f32_16x16x32_bf16 v[76:79], v[172:175], v[220:223], v[76:79]
	v_mfma_f32_16x16x32_bf16 v[128:131], v[168:171], v[200:203], v[128:131]
	v_mfma_f32_16x16x32_bf16 v[124:127], v[176:179], v[200:203], v[124:127]
	v_mfma_f32_16x16x32_bf16 v[116:119], v[168:171], v[208:211], v[116:119]
	v_mfma_f32_16x16x32_bf16 v[108:111], v[176:179], v[208:211], v[108:111]
	v_mfma_f32_16x16x32_bf16 v[100:103], v[168:171], v[216:219], v[100:103]
	v_mfma_f32_16x16x32_bf16 v[92:95], v[176:179], v[216:219], v[92:95]
	v_mfma_f32_16x16x32_bf16 v[84:87], v[168:171], v[224:227], v[84:87]
	v_mfma_f32_16x16x32_bf16 v[76:79], v[176:179], v[224:227], v[76:79]
	v_mfma_f32_16x16x32_bf16 v[120:123], v[180:183], v[196:199], v[120:123]
	v_mfma_f32_16x16x32_bf16 v[112:115], v[188:191], v[196:199], v[112:115]
	v_mfma_f32_16x16x32_bf16 v[104:107], v[180:183], v[204:207], v[104:107]
	v_mfma_f32_16x16x32_bf16 v[96:99], v[188:191], v[204:207], v[96:99]
	v_mfma_f32_16x16x32_bf16 v[88:91], v[180:183], v[212:215], v[88:91]
	v_mfma_f32_16x16x32_bf16 v[80:83], v[188:191], v[212:215], v[80:83]
	v_mfma_f32_16x16x32_bf16 v[72:75], v[180:183], v[220:223], v[72:75]
	v_mfma_f32_16x16x32_bf16 v[68:71], v[188:191], v[220:223], v[68:71]
	v_mfma_f32_16x16x32_bf16 v[120:123], v[184:187], v[200:203], v[120:123]
	v_mfma_f32_16x16x32_bf16 v[112:115], v[192:195], v[200:203], v[112:115]
	v_mfma_f32_16x16x32_bf16 v[104:107], v[184:187], v[208:211], v[104:107]
	v_mfma_f32_16x16x32_bf16 v[96:99], v[192:195], v[208:211], v[96:99]
	v_mfma_f32_16x16x32_bf16 v[88:91], v[184:187], v[216:219], v[88:91]
	v_mfma_f32_16x16x32_bf16 v[80:83], v[192:195], v[216:219], v[80:83]
	v_mfma_f32_16x16x32_bf16 v[72:75], v[184:187], v[224:227], v[72:75]
	v_mfma_f32_16x16x32_bf16 v[68:71], v[192:195], v[224:227], v[68:71]
	s_setprio 0
	s_barrier
	s_add_i32 s43, s50, s10
	s_mov_b32 m0, s43
	ds_read_b128 v[196:199], v167 offset:16384
	ds_read_b128 v[200:203], v167 offset:17408
	ds_read_b128 v[204:207], v167 offset:18432
	ds_read_b128 v[208:211], v167 offset:19456
	ds_read_b128 v[212:215], v167 offset:20480
	ds_read_b128 v[216:219], v167 offset:21504
	ds_read_b128 v[220:223], v167 offset:22528
	ds_read_b128 v[224:227], v167 offset:23552
	global_load_lds_dwordx4 v2, s[46:47]
	s_add_i32 m0, s43, 0x2000
	s_add_u32 s50, s46, 0x80000
	s_addc_u32 s51, s47, 0
	s_add_i32 s33, s33, s10
	global_load_lds_dwordx4 v0, s[46:47]
	s_mov_b32 m0, s33
	s_nop 0
	global_load_lds_dwordx4 v2, s[50:51]
	s_add_i32 m0, s33, 0x2000
	s_nop 0
	global_load_lds_dwordx4 v0, s[50:51]
	s_mov_b32 m0, s12
	s_nop 0
	global_load_lds_dwordx4 v134, s[48:49]
	s_mov_b32 m0, s13
	s_nop 0
	global_load_lds_dwordx4 v132, s[48:49]
	s_waitcnt vmcnt(8)
	s_waitcnt lgkmcnt(0)
	s_barrier
	s_setprio 1
	s_waitcnt lgkmcnt(0)
	v_mfma_f32_16x16x32_bf16 v[64:67], v[154:157], v[196:199], v[64:67]
	v_mfma_f32_16x16x32_bf16 v[60:63], v[172:175], v[196:199], v[60:63]
	v_mfma_f32_16x16x32_bf16 v[52:55], v[154:157], v[204:207], v[52:55]
	v_mfma_f32_16x16x32_bf16 v[44:47], v[172:175], v[204:207], v[44:47]
	v_mfma_f32_16x16x32_bf16 v[36:39], v[154:157], v[212:215], v[36:39]
	v_mfma_f32_16x16x32_bf16 v[28:31], v[172:175], v[212:215], v[28:31]
	v_mfma_f32_16x16x32_bf16 v[20:23], v[154:157], v[220:223], v[20:23]
	v_mfma_f32_16x16x32_bf16 v[12:15], v[172:175], v[220:223], v[12:15]
	v_mfma_f32_16x16x32_bf16 v[64:67], v[168:171], v[200:203], v[64:67]
	v_mfma_f32_16x16x32_bf16 v[60:63], v[176:179], v[200:203], v[60:63]
	v_mfma_f32_16x16x32_bf16 v[52:55], v[168:171], v[208:211], v[52:55]
	v_mfma_f32_16x16x32_bf16 v[44:47], v[176:179], v[208:211], v[44:47]
	v_mfma_f32_16x16x32_bf16 v[36:39], v[168:171], v[216:219], v[36:39]
	v_mfma_f32_16x16x32_bf16 v[28:31], v[176:179], v[216:219], v[28:31]
	v_mfma_f32_16x16x32_bf16 v[20:23], v[168:171], v[224:227], v[20:23]
	v_mfma_f32_16x16x32_bf16 v[12:15], v[176:179], v[224:227], v[12:15]
	v_mfma_f32_16x16x32_bf16 v[56:59], v[180:183], v[196:199], v[56:59]
	v_mfma_f32_16x16x32_bf16 v[48:51], v[188:191], v[196:199], v[48:51]
	v_mfma_f32_16x16x32_bf16 v[40:43], v[180:183], v[204:207], v[40:43]
	v_mfma_f32_16x16x32_bf16 v[32:35], v[188:191], v[204:207], v[32:35]
	v_mfma_f32_16x16x32_bf16 v[24:27], v[180:183], v[212:215], v[24:27]
	v_mfma_f32_16x16x32_bf16 v[16:19], v[188:191], v[212:215], v[16:19]
	v_mfma_f32_16x16x32_bf16 v[8:11], v[180:183], v[220:223], v[8:11]
	v_mfma_f32_16x16x32_bf16 v[4:7], v[188:191], v[220:223], v[4:7]
	v_mfma_f32_16x16x32_bf16 v[56:59], v[184:187], v[200:203], v[56:59]
	v_mfma_f32_16x16x32_bf16 v[48:51], v[192:195], v[200:203], v[48:51]
	v_mfma_f32_16x16x32_bf16 v[40:43], v[184:187], v[208:211], v[40:43]
	v_mfma_f32_16x16x32_bf16 v[32:35], v[192:195], v[208:211], v[32:35]
	v_mfma_f32_16x16x32_bf16 v[24:27], v[184:187], v[216:219], v[24:27]
	v_mfma_f32_16x16x32_bf16 v[16:19], v[192:195], v[216:219], v[16:19]
	v_mfma_f32_16x16x32_bf16 v[8:11], v[184:187], v[224:227], v[8:11]
	v_mfma_f32_16x16x32_bf16 v[4:7], v[192:195], v[224:227], v[4:7]
	s_setprio 0
	s_barrier
	s_add_i32 s33, 0, 0x18000
	s_add_i32 s43, 0, 0x1c000
	ds_read_b128 v[154:157], v229 offset:32768
	ds_read_b128 v[168:171], v229 offset:33792
	ds_read_b128 v[172:175], v229 offset:34816
	ds_read_b128 v[176:179], v229 offset:35840
	ds_read_b128 v[180:183], v229 offset:49152
	ds_read_b128 v[184:187], v229 offset:50176
	ds_read_b128 v[188:191], v229 offset:51200
	ds_read_b128 v[192:195], v229 offset:52224
	s_add_u32 s48, s48, 0x80000
	s_addc_u32 s49, s49, 0
	s_mov_b32 m0, s14
	ds_read_b128 v[196:199], v167 offset:32768
	ds_read_b128 v[200:203], v167 offset:33792
	ds_read_b128 v[204:207], v167 offset:34816
	ds_read_b128 v[208:211], v167 offset:35840
	ds_read_b128 v[212:215], v167 offset:36864
	ds_read_b128 v[216:219], v167 offset:37888
	ds_read_b128 v[220:223], v167 offset:38912
	ds_read_b128 v[224:227], v167 offset:39936
	global_load_lds_dwordx4 v134, s[48:49]
	s_mov_b32 m0, s15
	s_nop 0
	global_load_lds_dwordx4 v132, s[48:49]
	s_waitcnt vmcnt(8)
	s_waitcnt lgkmcnt(0)
	s_barrier
	s_setprio 1
	s_waitcnt lgkmcnt(0)
	v_mfma_f32_16x16x32_bf16 v[128:131], v[154:157], v[196:199], v[128:131]
	v_mfma_f32_16x16x32_bf16 v[124:127], v[172:175], v[196:199], v[124:127]
	v_mfma_f32_16x16x32_bf16 v[116:119], v[154:157], v[204:207], v[116:119]
	v_mfma_f32_16x16x32_bf16 v[108:111], v[172:175], v[204:207], v[108:111]
	v_mfma_f32_16x16x32_bf16 v[100:103], v[154:157], v[212:215], v[100:103]
	v_mfma_f32_16x16x32_bf16 v[92:95], v[172:175], v[212:215], v[92:95]
	v_mfma_f32_16x16x32_bf16 v[84:87], v[154:157], v[220:223], v[84:87]
	v_mfma_f32_16x16x32_bf16 v[76:79], v[172:175], v[220:223], v[76:79]
	v_mfma_f32_16x16x32_bf16 v[128:131], v[168:171], v[200:203], v[128:131]
	v_mfma_f32_16x16x32_bf16 v[124:127], v[176:179], v[200:203], v[124:127]
	v_mfma_f32_16x16x32_bf16 v[116:119], v[168:171], v[208:211], v[116:119]
	v_mfma_f32_16x16x32_bf16 v[108:111], v[176:179], v[208:211], v[108:111]
	v_mfma_f32_16x16x32_bf16 v[100:103], v[168:171], v[216:219], v[100:103]
	v_mfma_f32_16x16x32_bf16 v[92:95], v[176:179], v[216:219], v[92:95]
	v_mfma_f32_16x16x32_bf16 v[84:87], v[168:171], v[224:227], v[84:87]
	v_mfma_f32_16x16x32_bf16 v[76:79], v[176:179], v[224:227], v[76:79]
	v_mfma_f32_16x16x32_bf16 v[120:123], v[180:183], v[196:199], v[120:123]
	v_mfma_f32_16x16x32_bf16 v[112:115], v[188:191], v[196:199], v[112:115]
	v_mfma_f32_16x16x32_bf16 v[104:107], v[180:183], v[204:207], v[104:107]
	v_mfma_f32_16x16x32_bf16 v[96:99], v[188:191], v[204:207], v[96:99]
	v_mfma_f32_16x16x32_bf16 v[88:91], v[180:183], v[212:215], v[88:91]
	v_mfma_f32_16x16x32_bf16 v[80:83], v[188:191], v[212:215], v[80:83]
	v_mfma_f32_16x16x32_bf16 v[72:75], v[180:183], v[220:223], v[72:75]
	v_mfma_f32_16x16x32_bf16 v[68:71], v[188:191], v[220:223], v[68:71]
	v_mfma_f32_16x16x32_bf16 v[120:123], v[184:187], v[200:203], v[120:123]
	v_mfma_f32_16x16x32_bf16 v[112:115], v[192:195], v[200:203], v[112:115]
	v_mfma_f32_16x16x32_bf16 v[104:107], v[184:187], v[208:211], v[104:107]
	v_mfma_f32_16x16x32_bf16 v[96:99], v[192:195], v[208:211], v[96:99]
	v_mfma_f32_16x16x32_bf16 v[88:91], v[184:187], v[216:219], v[88:91]
	v_mfma_f32_16x16x32_bf16 v[80:83], v[192:195], v[216:219], v[80:83]
	v_mfma_f32_16x16x32_bf16 v[72:75], v[184:187], v[224:227], v[72:75]
	v_mfma_f32_16x16x32_bf16 v[68:71], v[192:195], v[224:227], v[68:71]
	s_setprio 0
	s_barrier
	s_add_i32 s33, s33, s10
	s_mov_b32 m0, s33
	ds_read_b128 v[196:199], v167 offset:49152
	ds_read_b128 v[200:203], v167 offset:50176
	ds_read_b128 v[204:207], v167 offset:51200
	ds_read_b128 v[208:211], v167 offset:52224
	ds_read_b128 v[212:215], v167 offset:53248
	ds_read_b128 v[216:219], v167 offset:54272
	ds_read_b128 v[220:223], v167 offset:55296
	ds_read_b128 v[224:227], v167 offset:56320
	s_add_u32 s100, s46, 0x80
	s_addc_u32 s101, s47, 0
	global_load_lds_dwordx4 v2, s[100:101]
	s_add_i32 m0, s33, 0x2000
	s_add_u32 s46, s46, 0x80080
	s_addc_u32 s47, s47, 0
	s_add_i32 s33, s43, s10
	s_add_u32 s100, s46, 0xfff80000
	s_addc_u32 s101, s47, -1
	global_load_lds_dwordx4 v0, s[100:101]
	s_mov_b32 m0, s33
	s_nop 0
	global_load_lds_dwordx4 v2, s[46:47]
	s_add_i32 m0, s33, 0x2000
	s_nop 0
	global_load_lds_dwordx4 v0, s[46:47]
	s_mov_b32 m0, s16
	s_nop 0
	s_add_u32 s100, s48, 0xfff80080
	s_addc_u32 s101, s49, -1
	global_load_lds_dwordx4 v134, s[100:101]
	s_mov_b32 m0, s17
	s_nop 0
	s_add_u32 s100, s48, 0xfff80080
	s_addc_u32 s101, s49, -1
	global_load_lds_dwordx4 v132, s[100:101]
	s_add_i32 s35, s35, 2
	s_add_u32 s31, s31, 0x100
	s_addc_u32 s34, s34, 0
	s_add_u32 s44, s44, 0x100
	s_addc_u32 s45, s45, 0
	s_add_u32 s33, s44, 0xfff80080
	s_addc_u32 s43, s45, -1
	s_cmp_eq_u32 s35, 28
	s_cselect_b32 s49, s27, s43
	s_cselect_b32 s48, s28, s33
	s_cselect_b32 s47, s25, s34
	s_cselect_b32 s46, s29, s31
	s_cmp_gt_u32 s35, 29
	s_waitcnt vmcnt(8)
	s_waitcnt lgkmcnt(0)
	s_barrier
	s_setprio 1
	s_waitcnt lgkmcnt(0)
	v_mfma_f32_16x16x32_bf16 v[64:67], v[154:157], v[196:199], v[64:67]
	v_mfma_f32_16x16x32_bf16 v[60:63], v[172:175], v[196:199], v[60:63]
	v_mfma_f32_16x16x32_bf16 v[52:55], v[154:157], v[204:207], v[52:55]
	v_mfma_f32_16x16x32_bf16 v[44:47], v[172:175], v[204:207], v[44:47]
	v_mfma_f32_16x16x32_bf16 v[36:39], v[154:157], v[212:215], v[36:39]
	v_mfma_f32_16x16x32_bf16 v[28:31], v[172:175], v[212:215], v[28:31]
	v_mfma_f32_16x16x32_bf16 v[20:23], v[154:157], v[220:223], v[20:23]
	v_mfma_f32_16x16x32_bf16 v[12:15], v[172:175], v[220:223], v[12:15]
	v_mfma_f32_16x16x32_bf16 v[64:67], v[168:171], v[200:203], v[64:67]
	v_mfma_f32_16x16x32_bf16 v[60:63], v[176:179], v[200:203], v[60:63]
	v_mfma_f32_16x16x32_bf16 v[52:55], v[168:171], v[208:211], v[52:55]
	v_mfma_f32_16x16x32_bf16 v[44:47], v[176:179], v[208:211], v[44:47]
	v_mfma_f32_16x16x32_bf16 v[36:39], v[168:171], v[216:219], v[36:39]
	v_mfma_f32_16x16x32_bf16 v[28:31], v[176:179], v[216:219], v[28:31]
	v_mfma_f32_16x16x32_bf16 v[20:23], v[168:171], v[224:227], v[20:23]
	v_mfma_f32_16x16x32_bf16 v[12:15], v[176:179], v[224:227], v[12:15]
	v_mfma_f32_16x16x32_bf16 v[56:59], v[180:183], v[196:199], v[56:59]
	v_mfma_f32_16x16x32_bf16 v[48:51], v[188:191], v[196:199], v[48:51]
	v_mfma_f32_16x16x32_bf16 v[40:43], v[180:183], v[204:207], v[40:43]
	v_mfma_f32_16x16x32_bf16 v[32:35], v[188:191], v[204:207], v[32:35]
	v_mfma_f32_16x16x32_bf16 v[24:27], v[180:183], v[212:215], v[24:27]
	v_mfma_f32_16x16x32_bf16 v[16:19], v[188:191], v[212:215], v[16:19]
	v_mfma_f32_16x16x32_bf16 v[8:11], v[180:183], v[220:223], v[8:11]
	v_mfma_f32_16x16x32_bf16 v[4:7], v[188:191], v[220:223], v[4:7]
	v_mfma_f32_16x16x32_bf16 v[56:59], v[184:187], v[200:203], v[56:59]
	v_mfma_f32_16x16x32_bf16 v[48:51], v[192:195], v[200:203], v[48:51]
	v_mfma_f32_16x16x32_bf16 v[40:43], v[184:187], v[208:211], v[40:43]
	v_mfma_f32_16x16x32_bf16 v[32:35], v[192:195], v[208:211], v[32:35]
	v_mfma_f32_16x16x32_bf16 v[24:27], v[184:187], v[216:219], v[24:27]
	v_mfma_f32_16x16x32_bf16 v[16:19], v[192:195], v[216:219], v[16:19]
	v_mfma_f32_16x16x32_bf16 v[8:11], v[184:187], v[224:227], v[8:11]
	v_mfma_f32_16x16x32_bf16 v[4:7], v[192:195], v[224:227], v[4:7]
	s_setprio 0
	s_barrier
	s_cbranch_scc0 .LBB0_342
	s_and_b64 vcc, exec, s[22:23]
	s_cbranch_vccz .LBB0_345
	s_nop 0

.LBB0_1063:
	v_add_u32_e32 v229, 0x10000, v163
	s_add_i32 s71, s71, 1
	s_cmp_gt_u32 s71, 1
	s_cselect_b32 s32, 1, 0
	s_cmp_lt_u32 s71, 11
	s_cselect_b64 s[36:37], -1, 0
	s_add_i32 s24, s4, 4
	s_mov_b32 s26, s42
.LBB0_1065:
	s_ashr_i32 s27, s26, 31
	s_lshl_b64 s[6:7], s[26:27], 20
	s_add_u32 s38, s52, s6
	s_addc_u32 s39, s53, s7
	s_and_b64 s[6:7], s[36:37], exec
	s_cselect_b32 s5, s39, s47
	s_cselect_b32 s6, s38, s46
	s_ashr_i32 s25, s24, 31
	s_lshl_b64 s[8:9], s[24:25], 20
	s_add_u32 s40, s54, s8
	s_addc_u32 s41, s55, s9
	s_and_b64 s[8:9], s[36:37], exec
	s_cselect_b32 s7, s41, s45
	s_cselect_b32 s8, s40, s44
	s_add_u32 s9, s44, 0x100
	s_addc_u32 s10, s45, 0
	s_add_u32 s44, s46, 0x80080
	s_addc_u32 s45, s47, 0
	s_mov_b32 s11, -2
	s_add_u32 s12, s44, 0xfff80080
	s_addc_u32 s13, s45, -1
	s_add_i32 s14, 0, 0x10000
	s_cmp_eq_u32 s11, 28
	s_cselect_b32 s49, s5, s13
	s_cselect_b32 s48, s6, s12
	s_cselect_b32 s47, s7, s10
	s_cselect_b32 s46, s8, s9
	s_add_i32 s15, 0, 0x14000
	ds_read_b128 v[142:145], v229
	ds_read_b128 v[146:149], v229 offset:1024
	ds_read_b128 v[150:153], v229 offset:2048
	ds_read_b128 v[154:157], v229 offset:3072
	ds_read_b128 v[168:171], v229 offset:16384
	ds_read_b128 v[172:175], v229 offset:17408
	ds_read_b128 v[176:179], v229 offset:18432
	ds_read_b128 v[180:183], v229 offset:19456
	s_add_i32 m0, s60, 0xc000
	ds_read_b128 v[184:187], v167
	ds_read_b128 v[188:191], v167 offset:1024
	ds_read_b128 v[192:195], v167 offset:2048
	ds_read_b128 v[196:199], v167 offset:3072
	ds_read_b128 v[200:203], v167 offset:4096
	ds_read_b128 v[204:207], v167 offset:5120
	ds_read_b128 v[208:211], v167 offset:6144
	ds_read_b128 v[212:215], v167 offset:7168
	global_load_lds_dwordx4 v140, s[44:45]
	s_add_i32 m0, s60, 0xe000
	s_nop 0
	global_load_lds_dwordx4 v138, s[44:45]
	s_cmp_lg_u32 s32, 0
	s_cbranch_scc1 .Lgu_skip1_p
	s_waitcnt vmcnt(8)

.Lgu_skip2_p:
	s_mov_b32 s32, 0
	s_waitcnt lgkmcnt(0)
	s_barrier
	s_setprio 1
	s_waitcnt lgkmcnt(0)
	v_mfma_f32_16x16x32_bf16 v[64:67], v[142:145], v[184:187], 0
	v_mfma_f32_16x16x32_bf16 v[56:59], v[150:153], v[184:187], 0
	v_mfma_f32_16x16x32_bf16 v[48:51], v[142:145], v[192:195], 0
	v_mfma_f32_16x16x32_bf16 v[40:43], v[150:153], v[192:195], 0
	v_mfma_f32_16x16x32_bf16 v[32:35], v[142:145], v[200:203], 0
	v_mfma_f32_16x16x32_bf16 v[24:27], v[150:153], v[200:203], 0
	v_mfma_f32_16x16x32_bf16 v[16:19], v[142:145], v[208:211], 0
	v_mfma_f32_16x16x32_bf16 v[8:11], v[150:153], v[208:211], 0
	v_mfma_f32_16x16x32_bf16 v[64:67], v[146:149], v[188:191], v[64:67]
	v_mfma_f32_16x16x32_bf16 v[56:59], v[154:157], v[188:191], v[56:59]
	v_mfma_f32_16x16x32_bf16 v[48:51], v[146:149], v[196:199], v[48:51]
	v_mfma_f32_16x16x32_bf16 v[40:43], v[154:157], v[196:199], v[40:43]
	v_mfma_f32_16x16x32_bf16 v[32:35], v[146:149], v[204:207], v[32:35]
	v_mfma_f32_16x16x32_bf16 v[24:27], v[154:157], v[204:207], v[24:27]
	v_mfma_f32_16x16x32_bf16 v[16:19], v[146:149], v[212:215], v[16:19]
	v_mfma_f32_16x16x32_bf16 v[8:11], v[154:157], v[212:215], v[8:11]
	v_mfma_f32_16x16x32_bf16 v[60:63], v[168:171], v[184:187], 0
	v_mfma_f32_16x16x32_bf16 v[52:55], v[176:179], v[184:187], 0
	v_mfma_f32_16x16x32_bf16 v[44:47], v[168:171], v[192:195], 0
	v_mfma_f32_16x16x32_bf16 v[36:39], v[176:179], v[192:195], 0
	v_mfma_f32_16x16x32_bf16 v[28:31], v[168:171], v[200:203], 0
	v_mfma_f32_16x16x32_bf16 v[20:23], v[176:179], v[200:203], 0
	v_mfma_f32_16x16x32_bf16 v[12:15], v[168:171], v[208:211], 0
	v_mfma_f32_16x16x32_bf16 v[4:7], v[176:179], v[208:211], 0
	v_mfma_f32_16x16x32_bf16 v[60:63], v[172:175], v[188:191], v[60:63]
	v_mfma_f32_16x16x32_bf16 v[52:55], v[180:183], v[188:191], v[52:55]
	v_mfma_f32_16x16x32_bf16 v[44:47], v[172:175], v[196:199], v[44:47]
	v_mfma_f32_16x16x32_bf16 v[36:39], v[180:183], v[196:199], v[36:39]
	v_mfma_f32_16x16x32_bf16 v[28:31], v[172:175], v[204:207], v[28:31]
	v_mfma_f32_16x16x32_bf16 v[20:23], v[180:183], v[204:207], v[20:23]
	v_mfma_f32_16x16x32_bf16 v[12:15], v[172:175], v[212:215], v[12:15]
	v_mfma_f32_16x16x32_bf16 v[4:7], v[180:183], v[212:215], v[4:7]
	s_setprio 0
	s_barrier
	s_add_i32 s14, 0, 0x18000
	s_add_i32 s15, 0, 0x1c000
	ds_read_b128 v[142:145], v229 offset:32768
	ds_read_b128 v[146:149], v229 offset:33792
	ds_read_b128 v[150:153], v229 offset:34816
	ds_read_b128 v[154:157], v229 offset:35840
	ds_read_b128 v[168:171], v229 offset:49152
	ds_read_b128 v[172:175], v229 offset:50176
	ds_read_b128 v[176:179], v229 offset:51200
	ds_read_b128 v[180:183], v229 offset:52224
	s_add_u32 s12, s48, 0x80000
	s_addc_u32 s13, s49, 0
	s_mov_b32 m0, s62
	ds_read_b128 v[184:187], v167 offset:32768
	ds_read_b128 v[188:191], v167 offset:33792
	ds_read_b128 v[192:195], v167 offset:34816
	ds_read_b128 v[196:199], v167 offset:35840
	ds_read_b128 v[200:203], v167 offset:36864
	ds_read_b128 v[204:207], v167 offset:37888
	ds_read_b128 v[208:211], v167 offset:38912
	ds_read_b128 v[212:215], v167 offset:39936
	global_load_lds_dwordx4 v134, s[12:13]
	s_mov_b32 m0, s63
	s_nop 0
	global_load_lds_dwordx4 v132, s[12:13]
	s_waitcnt vmcnt(8)
	s_waitcnt lgkmcnt(0)
	s_barrier
	s_setprio 1
	s_waitcnt lgkmcnt(0)
	v_mfma_f32_16x16x32_bf16 v[124:127], v[142:145], v[184:187], v[124:127]
	v_mfma_f32_16x16x32_bf16 v[120:123], v[150:153], v[184:187], v[120:123]
	v_mfma_f32_16x16x32_bf16 v[112:115], v[142:145], v[192:195], v[112:115]
	v_mfma_f32_16x16x32_bf16 v[104:107], v[150:153], v[192:195], v[104:107]
	v_mfma_f32_16x16x32_bf16 v[96:99], v[142:145], v[200:203], v[96:99]
	v_mfma_f32_16x16x32_bf16 v[88:91], v[150:153], v[200:203], v[88:91]
	v_mfma_f32_16x16x32_bf16 v[80:83], v[142:145], v[208:211], v[80:83]
	v_mfma_f32_16x16x32_bf16 v[72:75], v[150:153], v[208:211], v[72:75]
	v_mfma_f32_16x16x32_bf16 v[124:127], v[146:149], v[188:191], v[124:127]
	v_mfma_f32_16x16x32_bf16 v[120:123], v[154:157], v[188:191], v[120:123]
	v_mfma_f32_16x16x32_bf16 v[112:115], v[146:149], v[196:199], v[112:115]
	v_mfma_f32_16x16x32_bf16 v[104:107], v[154:157], v[196:199], v[104:107]
	v_mfma_f32_16x16x32_bf16 v[96:99], v[146:149], v[204:207], v[96:99]
	v_mfma_f32_16x16x32_bf16 v[88:91], v[154:157], v[204:207], v[88:91]
	v_mfma_f32_16x16x32_bf16 v[80:83], v[146:149], v[212:215], v[80:83]
	v_mfma_f32_16x16x32_bf16 v[72:75], v[154:157], v[212:215], v[72:75]
	v_mfma_f32_16x16x32_bf16 v[128:131], v[168:171], v[184:187], v[128:131]
	v_mfma_f32_16x16x32_bf16 v[116:119], v[176:179], v[184:187], v[116:119]
	v_mfma_f32_16x16x32_bf16 v[108:111], v[168:171], v[192:195], v[108:111]
	v_mfma_f32_16x16x32_bf16 v[100:103], v[176:179], v[192:195], v[100:103]
	v_mfma_f32_16x16x32_bf16 v[92:95], v[168:171], v[200:203], v[92:95]
	v_mfma_f32_16x16x32_bf16 v[84:87], v[176:179], v[200:203], v[84:87]
	v_mfma_f32_16x16x32_bf16 v[76:79], v[168:171], v[208:211], v[76:79]
	v_mfma_f32_16x16x32_bf16 v[68:71], v[176:179], v[208:211], v[68:71]
	v_mfma_f32_16x16x32_bf16 v[128:131], v[172:175], v[188:191], v[128:131]
	v_mfma_f32_16x16x32_bf16 v[116:119], v[180:183], v[188:191], v[116:119]
	v_mfma_f32_16x16x32_bf16 v[108:111], v[172:175], v[196:199], v[108:111]
	v_mfma_f32_16x16x32_bf16 v[100:103], v[180:183], v[196:199], v[100:103]
	v_mfma_f32_16x16x32_bf16 v[92:95], v[172:175], v[204:207], v[92:95]
	v_mfma_f32_16x16x32_bf16 v[84:87], v[180:183], v[204:207], v[84:87]
	v_mfma_f32_16x16x32_bf16 v[76:79], v[172:175], v[212:215], v[76:79]
	v_mfma_f32_16x16x32_bf16 v[68:71], v[180:183], v[212:215], v[68:71]
	s_setprio 0
	s_barrier
	s_add_i32 s12, s14, s56
	s_mov_b32 m0, s12
	ds_read_b128 v[184:187], v167 offset:49152
	ds_read_b128 v[188:191], v167 offset:50176
	ds_read_b128 v[192:195], v167 offset:51200
	ds_read_b128 v[196:199], v167 offset:52224
	ds_read_b128 v[200:203], v167 offset:53248
	ds_read_b128 v[204:207], v167 offset:54272
	ds_read_b128 v[208:211], v167 offset:55296
	ds_read_b128 v[212:215], v167 offset:56320
	s_add_u32 s100, s46, 0x80
	s_addc_u32 s101, s47, 0
	global_load_lds_dwordx4 v2, s[100:101]
	s_add_i32 m0, s12, 0x2000
	s_add_u32 s12, s46, 0x80080
	s_addc_u32 s13, s47, 0
	s_add_i32 s14, s15, s56
	s_add_u32 s100, s46, 0x80
	s_addc_u32 s101, s47, 0
	global_load_lds_dwordx4 v0, s[100:101]
	s_mov_b32 m0, s14
	s_nop 0
	global_load_lds_dwordx4 v2, s[12:13]
	s_add_i32 m0, s14, 0x2000
	s_nop 0
	global_load_lds_dwordx4 v0, s[12:13]
	s_mov_b32 m0, s64
	s_nop 0
	s_add_u32 s100, s48, 0x80
	s_addc_u32 s101, s49, 0
	global_load_lds_dwordx4 v134, s[100:101]
	s_mov_b32 m0, s65
	s_nop 0
	s_add_u32 s100, s48, 0x80
	s_addc_u32 s101, s49, 0
	global_load_lds_dwordx4 v132, s[100:101]
	s_add_i32 s11, s11, 2
	s_add_u32 s9, s9, 0x100
	s_addc_u32 s10, s10, 0
	s_add_u32 s44, s44, 0x100
	s_addc_u32 s45, s45, 0
	s_add_u32 s12, s44, 0xfff80080
	s_addc_u32 s13, s45, -1
	s_cmp_eq_u32 s11, 28
	s_cselect_b32 s49, s5, s13
	s_cselect_b32 s48, s6, s12
	s_cselect_b32 s47, s7, s10
	s_cselect_b32 s46, s8, s9
	s_waitcnt vmcnt(8)
	s_waitcnt lgkmcnt(0)
	s_barrier
	s_setprio 1
	s_waitcnt lgkmcnt(0)
	v_mfma_f32_16x16x32_bf16 v[64:67], v[142:145], v[184:187], v[64:67]
	v_mfma_f32_16x16x32_bf16 v[56:59], v[150:153], v[184:187], v[56:59]
	v_mfma_f32_16x16x32_bf16 v[48:51], v[142:145], v[192:195], v[48:51]
	v_mfma_f32_16x16x32_bf16 v[40:43], v[150:153], v[192:195], v[40:43]
	v_mfma_f32_16x16x32_bf16 v[32:35], v[142:145], v[200:203], v[32:35]
	v_mfma_f32_16x16x32_bf16 v[24:27], v[150:153], v[200:203], v[24:27]
	v_mfma_f32_16x16x32_bf16 v[16:19], v[142:145], v[208:211], v[16:19]
	v_mfma_f32_16x16x32_bf16 v[8:11], v[150:153], v[208:211], v[8:11]
	v_mfma_f32_16x16x32_bf16 v[64:67], v[146:149], v[188:191], v[64:67]
	v_mfma_f32_16x16x32_bf16 v[56:59], v[154:157], v[188:191], v[56:59]
	v_mfma_f32_16x16x32_bf16 v[48:51], v[146:149], v[196:199], v[48:51]
	v_mfma_f32_16x16x32_bf16 v[40:43], v[154:157], v[196:199], v[40:43]
	v_mfma_f32_16x16x32_bf16 v[32:35], v[146:149], v[204:207], v[32:35]
	v_mfma_f32_16x16x32_bf16 v[24:27], v[154:157], v[204:207], v[24:27]
	v_mfma_f32_16x16x32_bf16 v[16:19], v[146:149], v[212:215], v[16:19]
	v_mfma_f32_16x16x32_bf16 v[8:11], v[154:157], v[212:215], v[8:11]
	v_mfma_f32_16x16x32_bf16 v[60:63], v[168:171], v[184:187], v[60:63]
	v_mfma_f32_16x16x32_bf16 v[52:55], v[176:179], v[184:187], v[52:55]
	v_mfma_f32_16x16x32_bf16 v[44:47], v[168:171], v[192:195], v[44:47]
	v_mfma_f32_16x16x32_bf16 v[36:39], v[176:179], v[192:195], v[36:39]
	v_mfma_f32_16x16x32_bf16 v[28:31], v[168:171], v[200:203], v[28:31]
	v_mfma_f32_16x16x32_bf16 v[20:23], v[176:179], v[200:203], v[20:23]
	v_mfma_f32_16x16x32_bf16 v[12:15], v[168:171], v[208:211], v[12:15]
	v_mfma_f32_16x16x32_bf16 v[4:7], v[176:179], v[208:211], v[4:7]
	v_mfma_f32_16x16x32_bf16 v[60:63], v[172:175], v[188:191], v[60:63]
	v_mfma_f32_16x16x32_bf16 v[52:55], v[180:183], v[188:191], v[52:55]
	v_mfma_f32_16x16x32_bf16 v[44:47], v[172:175], v[196:199], v[44:47]
	v_mfma_f32_16x16x32_bf16 v[36:39], v[180:183], v[196:199], v[36:39]
	v_mfma_f32_16x16x32_bf16 v[28:31], v[172:175], v[204:207], v[28:31]
	v_mfma_f32_16x16x32_bf16 v[20:23], v[180:183], v[204:207], v[20:23]
	v_mfma_f32_16x16x32_bf16 v[12:15], v[172:175], v[212:215], v[12:15]
	v_mfma_f32_16x16x32_bf16 v[4:7], v[180:183], v[212:215], v[4:7]
	s_setprio 0
	s_barrier
.LBB0_1066:
	s_add_i32 s14, 0, 0x10000
	s_add_i32 s15, 0, 0x14000
	ds_read_b128 v[142:145], v229
	ds_read_b128 v[146:149], v229 offset:1024
	ds_read_b128 v[150:153], v229 offset:2048
	ds_read_b128 v[154:157], v229 offset:3072
	ds_read_b128 v[168:171], v229 offset:16384
	ds_read_b128 v[172:175], v229 offset:17408
	ds_read_b128 v[176:179], v229 offset:18432
	ds_read_b128 v[180:183], v229 offset:19456
	s_add_i32 m0, s60, 0xc000
	ds_read_b128 v[184:187], v167
	ds_read_b128 v[188:191], v167 offset:1024
	ds_read_b128 v[192:195], v167 offset:2048
	ds_read_b128 v[196:199], v167 offset:3072
	ds_read_b128 v[200:203], v167 offset:4096
	ds_read_b128 v[204:207], v167 offset:5120
	ds_read_b128 v[208:211], v167 offset:6144
	ds_read_b128 v[212:215], v167 offset:7168
	global_load_lds_dwordx4 v140, s[44:45]
	s_add_i32 m0, s60, 0xe000
	s_nop 0
	global_load_lds_dwordx4 v138, s[44:45]
	s_waitcnt vmcnt(8)
	s_waitcnt lgkmcnt(0)
	s_barrier
	s_setprio 1
	s_waitcnt lgkmcnt(0)
	v_mfma_f32_16x16x32_bf16 v[124:127], v[142:145], v[184:187], v[124:127]
	v_mfma_f32_16x16x32_bf16 v[120:123], v[150:153], v[184:187], v[120:123]
	v_mfma_f32_16x16x32_bf16 v[112:115], v[142:145], v[192:195], v[112:115]
	v_mfma_f32_16x16x32_bf16 v[104:107], v[150:153], v[192:195], v[104:107]
	v_mfma_f32_16x16x32_bf16 v[96:99], v[142:145], v[200:203], v[96:99]
	v_mfma_f32_16x16x32_bf16 v[88:91], v[150:153], v[200:203], v[88:91]
	v_mfma_f32_16x16x32_bf16 v[80:83], v[142:145], v[208:211], v[80:83]
	v_mfma_f32_16x16x32_bf16 v[72:75], v[150:153], v[208:211], v[72:75]
	v_mfma_f32_16x16x32_bf16 v[124:127], v[146:149], v[188:191], v[124:127]
	v_mfma_f32_16x16x32_bf16 v[120:123], v[154:157], v[188:191], v[120:123]
	v_mfma_f32_16x16x32_bf16 v[112:115], v[146:149], v[196:199], v[112:115]
	v_mfma_f32_16x16x32_bf16 v[104:107], v[154:157], v[196:199], v[104:107]
	v_mfma_f32_16x16x32_bf16 v[96:99], v[146:149], v[204:207], v[96:99]
	v_mfma_f32_16x16x32_bf16 v[88:91], v[154:157], v[204:207], v[88:91]
	v_mfma_f32_16x16x32_bf16 v[80:83], v[146:149], v[212:215], v[80:83]
	v_mfma_f32_16x16x32_bf16 v[72:75], v[154:157], v[212:215], v[72:75]
	v_mfma_f32_16x16x32_bf16 v[128:131], v[168:171], v[184:187], v[128:131]
	v_mfma_f32_16x16x32_bf16 v[116:119], v[176:179], v[184:187], v[116:119]
	v_mfma_f32_16x16x32_bf16 v[108:111], v[168:171], v[192:195], v[108:111]
	v_mfma_f32_16x16x32_bf16 v[100:103], v[176:179], v[192:195], v[100:103]
	v_mfma_f32_16x16x32_bf16 v[92:95], v[168:171], v[200:203], v[92:95]
	v_mfma_f32_16x16x32_bf16 v[84:87], v[176:179], v[200:203], v[84:87]
	v_mfma_f32_16x16x32_bf16 v[76:79], v[168:171], v[208:211], v[76:79]
	v_mfma_f32_16x16x32_bf16 v[68:71], v[176:179], v[208:211], v[68:71]
	v_mfma_f32_16x16x32_bf16 v[128:131], v[172:175], v[188:191], v[128:131]
	v_mfma_f32_16x16x32_bf16 v[116:119], v[180:183], v[188:191], v[116:119]
	v_mfma_f32_16x16x32_bf16 v[108:111], v[172:175], v[196:199], v[108:111]
	v_mfma_f32_16x16x32_bf16 v[100:103], v[180:183], v[196:199], v[100:103]
	v_mfma_f32_16x16x32_bf16 v[92:95], v[172:175], v[204:207], v[92:95]
	v_mfma_f32_16x16x32_bf16 v[84:87], v[180:183], v[204:207], v[84:87]
	v_mfma_f32_16x16x32_bf16 v[76:79], v[172:175], v[212:215], v[76:79]
	v_mfma_f32_16x16x32_bf16 v[68:71], v[180:183], v[212:215], v[68:71]
	s_setprio 0
	s_barrier
	s_add_i32 s12, s14, s56
	s_mov_b32 m0, s12
	ds_read_b128 v[184:187], v167 offset:16384
	ds_read_b128 v[188:191], v167 offset:17408
	ds_read_b128 v[192:195], v167 offset:18432
	ds_read_b128 v[196:199], v167 offset:19456
	ds_read_b128 v[200:203], v167 offset:20480
	ds_read_b128 v[204:207], v167 offset:21504
	ds_read_b128 v[208:211], v167 offset:22528
	ds_read_b128 v[212:215], v167 offset:23552
	global_load_lds_dwordx4 v2, s[46:47]
	s_add_i32 m0, s12, 0x2000
	s_add_u32 s12, s46, 0x80000
	s_addc_u32 s13, s47, 0
	s_add_i32 s14, s15, s56
	global_load_lds_dwordx4 v0, s[46:47]
	s_mov_b32 m0, s14
	s_nop 0
	global_load_lds_dwordx4 v2, s[12:13]
	s_add_i32 m0, s14, 0x2000
	s_nop 0
	global_load_lds_dwordx4 v0, s[12:13]
	s_mov_b32 m0, s60
	s_nop 0
	global_load_lds_dwordx4 v134, s[48:49]
	s_mov_b32 m0, s61
	s_nop 0
	global_load_lds_dwordx4 v132, s[48:49]
	s_waitcnt vmcnt(8)
	s_waitcnt lgkmcnt(0)
	s_barrier
	s_setprio 1
	s_waitcnt lgkmcnt(0)
	v_mfma_f32_16x16x32_bf16 v[64:67], v[142:145], v[184:187], v[64:67]
	v_mfma_f32_16x16x32_bf16 v[56:59], v[150:153], v[184:187], v[56:59]
	v_mfma_f32_16x16x32_bf16 v[48:51], v[142:145], v[192:195], v[48:51]
	v_mfma_f32_16x16x32_bf16 v[40:43], v[150:153], v[192:195], v[40:43]
	v_mfma_f32_16x16x32_bf16 v[32:35], v[142:145], v[200:203], v[32:35]
	v_mfma_f32_16x16x32_bf16 v[24:27], v[150:153], v[200:203], v[24:27]
	v_mfma_f32_16x16x32_bf16 v[16:19], v[142:145], v[208:211], v[16:19]
	v_mfma_f32_16x16x32_bf16 v[8:11], v[150:153], v[208:211], v[8:11]
	v_mfma_f32_16x16x32_bf16 v[64:67], v[146:149], v[188:191], v[64:67]
	v_mfma_f32_16x16x32_bf16 v[56:59], v[154:157], v[188:191], v[56:59]
	v_mfma_f32_16x16x32_bf16 v[48:51], v[146:149], v[196:199], v[48:51]
	v_mfma_f32_16x16x32_bf16 v[40:43], v[154:157], v[196:199], v[40:43]
	v_mfma_f32_16x16x32_bf16 v[32:35], v[146:149], v[204:207], v[32:35]
	v_mfma_f32_16x16x32_bf16 v[24:27], v[154:157], v[204:207], v[24:27]
	v_mfma_f32_16x16x32_bf16 v[16:19], v[146:149], v[212:215], v[16:19]
	v_mfma_f32_16x16x32_bf16 v[8:11], v[154:157], v[212:215], v[8:11]
	v_mfma_f32_16x16x32_bf16 v[60:63], v[168:171], v[184:187], v[60:63]
	v_mfma_f32_16x16x32_bf16 v[52:55], v[176:179], v[184:187], v[52:55]
	v_mfma_f32_16x16x32_bf16 v[44:47], v[168:171], v[192:195], v[44:47]
	v_mfma_f32_16x16x32_bf16 v[36:39], v[176:179], v[192:195], v[36:39]
	v_mfma_f32_16x16x32_bf16 v[28:31], v[168:171], v[200:203], v[28:31]
	v_mfma_f32_16x16x32_bf16 v[20:23], v[176:179], v[200:203], v[20:23]
	v_mfma_f32_16x16x32_bf16 v[12:15], v[168:171], v[208:211], v[12:15]
	v_mfma_f32_16x16x32_bf16 v[4:7], v[176:179], v[208:211], v[4:7]
	v_mfma_f32_16x16x32_bf16 v[60:63], v[172:175], v[188:191], v[60:63]
	v_mfma_f32_16x16x32_bf16 v[52:55], v[180:183], v[188:191], v[52:55]
	v_mfma_f32_16x16x32_bf16 v[44:47], v[172:175], v[196:199], v[44:47]
	v_mfma_f32_16x16x32_bf16 v[36:39], v[180:183], v[196:199], v[36:39]
	v_mfma_f32_16x16x32_bf16 v[28:31], v[172:175], v[204:207], v[28:31]
	v_mfma_f32_16x16x32_bf16 v[20:23], v[180:183], v[204:207], v[20:23]
	v_mfma_f32_16x16x32_bf16 v[12:15], v[172:175], v[212:215], v[12:15]
	v_mfma_f32_16x16x32_bf16 v[4:7], v[180:183], v[212:215], v[4:7]
	s_setprio 0
	s_barrier
	s_add_i32 s14, 0, 0x18000
	s_add_i32 s15, 0, 0x1c000
	ds_read_b128 v[142:145], v229 offset:32768
	ds_read_b128 v[146:149], v229 offset:33792
	ds_read_b128 v[150:153], v229 offset:34816
	ds_read_b128 v[154:157], v229 offset:35840
	ds_read_b128 v[168:171], v229 offset:49152
	ds_read_b128 v[172:175], v229 offset:50176
	ds_read_b128 v[176:179], v229 offset:51200
	ds_read_b128 v[180:183], v229 offset:52224
	s_add_u32 s12, s48, 0x80000
	s_addc_u32 s13, s49, 0
	s_mov_b32 m0, s62
	ds_read_b128 v[184:187], v167 offset:32768
	ds_read_b128 v[188:191], v167 offset:33792
	ds_read_b128 v[192:195], v167 offset:34816
	ds_read_b128 v[196:199], v167 offset:35840
	ds_read_b128 v[200:203], v167 offset:36864
	ds_read_b128 v[204:207], v167 offset:37888
	ds_read_b128 v[208:211], v167 offset:38912
	ds_read_b128 v[212:215], v167 offset:39936
	global_load_lds_dwordx4 v134, s[12:13]
	s_mov_b32 m0, s63
	s_nop 0
	global_load_lds_dwordx4 v132, s[12:13]
	s_waitcnt vmcnt(8)
	s_waitcnt lgkmcnt(0)
	s_barrier
	s_setprio 1
	s_waitcnt lgkmcnt(0)
	v_mfma_f32_16x16x32_bf16 v[124:127], v[142:145], v[184:187], v[124:127]
	v_mfma_f32_16x16x32_bf16 v[120:123], v[150:153], v[184:187], v[120:123]
	v_mfma_f32_16x16x32_bf16 v[112:115], v[142:145], v[192:195], v[112:115]
	v_mfma_f32_16x16x32_bf16 v[104:107], v[150:153], v[192:195], v[104:107]
	v_mfma_f32_16x16x32_bf16 v[96:99], v[142:145], v[200:203], v[96:99]
	v_mfma_f32_16x16x32_bf16 v[88:91], v[150:153], v[200:203], v[88:91]
	v_mfma_f32_16x16x32_bf16 v[80:83], v[142:145], v[208:211], v[80:83]
	v_mfma_f32_16x16x32_bf16 v[72:75], v[150:153], v[208:211], v[72:75]
	v_mfma_f32_16x16x32_bf16 v[124:127], v[146:149], v[188:191], v[124:127]
	v_mfma_f32_16x16x32_bf16 v[120:123], v[154:157], v[188:191], v[120:123]
	v_mfma_f32_16x16x32_bf16 v[112:115], v[146:149], v[196:199], v[112:115]
	v_mfma_f32_16x16x32_bf16 v[104:107], v[154:157], v[196:199], v[104:107]
	v_mfma_f32_16x16x32_bf16 v[96:99], v[146:149], v[204:207], v[96:99]
	v_mfma_f32_16x16x32_bf16 v[88:91], v[154:157], v[204:207], v[88:91]
	v_mfma_f32_16x16x32_bf16 v[80:83], v[146:149], v[212:215], v[80:83]
	v_mfma_f32_16x16x32_bf16 v[72:75], v[154:157], v[212:215], v[72:75]
	v_mfma_f32_16x16x32_bf16 v[128:131], v[168:171], v[184:187], v[128:131]
	v_mfma_f32_16x16x32_bf16 v[116:119], v[176:179], v[184:187], v[116:119]
	v_mfma_f32_16x16x32_bf16 v[108:111], v[168:171], v[192:195], v[108:111]
	v_mfma_f32_16x16x32_bf16 v[100:103], v[176:179], v[192:195], v[100:103]
	v_mfma_f32_16x16x32_bf16 v[92:95], v[168:171], v[200:203], v[92:95]
	v_mfma_f32_16x16x32_bf16 v[84:87], v[176:179], v[200:203], v[84:87]
	v_mfma_f32_16x16x32_bf16 v[76:79], v[168:171], v[208:211], v[76:79]
	v_mfma_f32_16x16x32_bf16 v[68:71], v[176:179], v[208:211], v[68:71]
	v_mfma_f32_16x16x32_bf16 v[128:131], v[172:175], v[188:191], v[128:131]
	v_mfma_f32_16x16x32_bf16 v[116:119], v[180:183], v[188:191], v[116:119]
	v_mfma_f32_16x16x32_bf16 v[108:111], v[172:175], v[196:199], v[108:111]
	v_mfma_f32_16x16x32_bf16 v[100:103], v[180:183], v[196:199], v[100:103]
	v_mfma_f32_16x16x32_bf16 v[92:95], v[172:175], v[204:207], v[92:95]
	v_mfma_f32_16x16x32_bf16 v[84:87], v[180:183], v[204:207], v[84:87]
	v_mfma_f32_16x16x32_bf16 v[76:79], v[172:175], v[212:215], v[76:79]
	v_mfma_f32_16x16x32_bf16 v[68:71], v[180:183], v[212:215], v[68:71]
	s_setprio 0
	s_barrier
	s_add_i32 s12, s14, s56
	s_mov_b32 m0, s12
	ds_read_b128 v[184:187], v167 offset:49152
	ds_read_b128 v[188:191], v167 offset:50176
	ds_read_b128 v[192:195], v167 offset:51200
	ds_read_b128 v[196:199], v167 offset:52224
	ds_read_b128 v[200:203], v167 offset:53248
	ds_read_b128 v[204:207], v167 offset:54272
	ds_read_b128 v[208:211], v167 offset:55296
	ds_read_b128 v[212:215], v167 offset:56320
	s_add_u32 s100, s46, 0x80
	s_addc_u32 s101, s47, 0
	global_load_lds_dwordx4 v2, s[100:101]
	s_add_i32 m0, s12, 0x2000
	s_add_u32 s12, s46, 0x80080
	s_addc_u32 s13, s47, 0
	s_add_i32 s14, s15, s56
	s_add_u32 s100, s46, 0x80
	s_addc_u32 s101, s47, 0
	global_load_lds_dwordx4 v0, s[100:101]
	s_mov_b32 m0, s14
	s_nop 0
	global_load_lds_dwordx4 v2, s[12:13]
	s_add_i32 m0, s14, 0x2000
	s_nop 0
	global_load_lds_dwordx4 v0, s[12:13]
	s_mov_b32 m0, s64
	s_nop 0
	s_add_u32 s100, s48, 0x80
	s_addc_u32 s101, s49, 0
	global_load_lds_dwordx4 v134, s[100:101]
	s_mov_b32 m0, s65
	s_nop 0
	s_add_u32 s100, s48, 0x80
	s_addc_u32 s101, s49, 0
	global_load_lds_dwordx4 v132, s[100:101]
	s_add_i32 s11, s11, 2
	s_add_u32 s9, s9, 0x100
	s_addc_u32 s10, s10, 0
	s_add_u32 s44, s44, 0x100
	s_addc_u32 s45, s45, 0
	s_add_u32 s12, s44, 0xfff80080
	s_addc_u32 s13, s45, -1
	s_cmp_eq_u32 s11, 28
	s_cselect_b32 s49, s5, s13
	s_cselect_b32 s48, s6, s12
	s_cselect_b32 s47, s7, s10
	s_cselect_b32 s46, s8, s9
	s_cmp_gt_u32 s11, 29
	s_waitcnt vmcnt(8)
	s_waitcnt lgkmcnt(0)
	s_barrier
	s_setprio 1
	s_waitcnt lgkmcnt(0)
	v_mfma_f32_16x16x32_bf16 v[64:67], v[142:145], v[184:187], v[64:67]
	v_mfma_f32_16x16x32_bf16 v[56:59], v[150:153], v[184:187], v[56:59]
	v_mfma_f32_16x16x32_bf16 v[48:51], v[142:145], v[192:195], v[48:51]
	v_mfma_f32_16x16x32_bf16 v[40:43], v[150:153], v[192:195], v[40:43]
	v_mfma_f32_16x16x32_bf16 v[32:35], v[142:145], v[200:203], v[32:35]
	v_mfma_f32_16x16x32_bf16 v[24:27], v[150:153], v[200:203], v[24:27]
	v_mfma_f32_16x16x32_bf16 v[16:19], v[142:145], v[208:211], v[16:19]
	v_mfma_f32_16x16x32_bf16 v[8:11], v[150:153], v[208:211], v[8:11]
	v_mfma_f32_16x16x32_bf16 v[64:67], v[146:149], v[188:191], v[64:67]
	v_mfma_f32_16x16x32_bf16 v[56:59], v[154:157], v[188:191], v[56:59]
	v_mfma_f32_16x16x32_bf16 v[48:51], v[146:149], v[196:199], v[48:51]
	v_mfma_f32_16x16x32_bf16 v[40:43], v[154:157], v[196:199], v[40:43]
	v_mfma_f32_16x16x32_bf16 v[32:35], v[146:149], v[204:207], v[32:35]
	v_mfma_f32_16x16x32_bf16 v[24:27], v[154:157], v[204:207], v[24:27]
	v_mfma_f32_16x16x32_bf16 v[16:19], v[146:149], v[212:215], v[16:19]
	v_mfma_f32_16x16x32_bf16 v[8:11], v[154:157], v[212:215], v[8:11]
	v_mfma_f32_16x16x32_bf16 v[60:63], v[168:171], v[184:187], v[60:63]
	v_mfma_f32_16x16x32_bf16 v[52:55], v[176:179], v[184:187], v[52:55]
	v_mfma_f32_16x16x32_bf16 v[44:47], v[168:171], v[192:195], v[44:47]
	v_mfma_f32_16x16x32_bf16 v[36:39], v[176:179], v[192:195], v[36:39]
	v_mfma_f32_16x16x32_bf16 v[28:31], v[168:171], v[200:203], v[28:31]
	v_mfma_f32_16x16x32_bf16 v[20:23], v[176:179], v[200:203], v[20:23]
	v_mfma_f32_16x16x32_bf16 v[12:15], v[168:171], v[208:211], v[12:15]
	v_mfma_f32_16x16x32_bf16 v[4:7], v[176:179], v[208:211], v[4:7]
	v_mfma_f32_16x16x32_bf16 v[60:63], v[172:175], v[188:191], v[60:63]
	v_mfma_f32_16x16x32_bf16 v[52:55], v[180:183], v[188:191], v[52:55]
	v_mfma_f32_16x16x32_bf16 v[44:47], v[172:175], v[196:199], v[44:47]
	v_mfma_f32_16x16x32_bf16 v[36:39], v[180:183], v[196:199], v[36:39]
	v_mfma_f32_16x16x32_bf16 v[28:31], v[172:175], v[204:207], v[28:31]
	v_mfma_f32_16x16x32_bf16 v[20:23], v[180:183], v[204:207], v[20:23]
	v_mfma_f32_16x16x32_bf16 v[12:15], v[172:175], v[212:215], v[12:15]
	v_mfma_f32_16x16x32_bf16 v[4:7], v[180:183], v[212:215], v[4:7]
	s_setprio 0
	s_barrier
	s_cbranch_scc0 .LBB0_1066
	s_and_b64 vcc, exec, s[22:23]
	s_cbranch_vccz .LBB0_1069
	s_nop 0
